# v94 + mLSTM scan S2: exponent subtractions read the hoisted per-row max registers directly (no copy + pad nop)
# speedup vs baseline: 1.0011x; 1.0011x over previous
.LBB0_218:
	s_or_b64 exec, exec, s[86:87]
	v_sub_f32_e32 v227, v124, v246
	v_sub_f32_e32 v228, v125, v246
	v_sub_f32_e32 v229, v126, v246
	v_exp_f32_e32 v227, v227
	v_exp_f32_e32 v228, v228
	v_sub_f32_e32 v230, v127, v246
	v_exp_f32_e32 v229, v229
	v_sub_f32_e32 v231, v120, v246
	v_exp_f32_e32 v230, v230
	v_sub_f32_e32 v232, v121, v246
	v_cndmask_b32_e64 v227, v227, 0, s[36:37]
	v_exp_f32_e32 v231, v231
	v_sub_f32_e32 v233, v122, v246
	v_cndmask_b32_e64 v228, 0, v228, s[38:39]
	v_fma_f32 v235, v112, v227, 0
	v_exp_f32_e32 v232, v232
	v_sub_f32_e32 v202, v123, v246
	v_fmac_f32_e32 v235, v113, v228
	v_cndmask_b32_e64 v229, v229, 0, s[40:41]
	v_exp_f32_e32 v233, v233
	v_fmac_f32_e32 v235, v114, v229
	v_cndmask_b32_e64 v230, v230, 0, s[42:43]
	v_exp_f32_e32 v202, v202
	v_fmac_f32_e32 v235, v115, v230
	v_cndmask_b32_e64 v231, v231, 0, s[18:19]
	v_fmac_f32_e32 v235, v100, v231
	v_cndmask_b32_e64 v232, v232, 0, s[44:45]
	v_fmac_f32_e32 v235, v101, v232
	v_cndmask_b32_e64 v233, v233, 0, s[46:47]
	v_fmac_f32_e32 v235, v102, v233
	v_cndmask_b32_e64 v234, v202, 0, s[48:49]
	v_fmac_f32_e32 v235, v103, v234
	v_mov_b32_e32 v202, v235
	s_nop 1
	v_permlane16_swap_b32_e32 v235, v202
	v_add_f32_e32 v235, v235, v202
	v_mov_b32_e32 v236, v235
	s_nop 1
	v_permlane32_swap_b32_e32 v235, v236
	s_and_saveexec_b64 s[86:87], s[8:9]
	s_cbranch_execz .LBB0_220
	v_add_f32_e32 v202, v235, v236
	ds_write_b32 v199, v202 offset:64
.LBB0_220:
	s_or_b64 exec, exec, s[86:87]
	v_sub_f32_e32 v235, v124, v247
	v_sub_f32_e32 v236, v125, v247
	v_sub_f32_e32 v237, v126, v247
	v_exp_f32_e32 v235, v235
	v_exp_f32_e32 v236, v236
	v_sub_f32_e32 v238, v127, v247
	v_exp_f32_e32 v237, v237
	v_sub_f32_e32 v239, v120, v247
	v_exp_f32_e32 v238, v238
	v_sub_f32_e32 v240, v121, v247
	v_cndmask_b32_e64 v235, v235, 0, s[50:51]
	v_exp_f32_e32 v239, v239
	v_sub_f32_e32 v241, v122, v247
	v_cndmask_b32_e64 v236, 0, v236, s[52:53]
	v_fma_f32 v243, v104, v235, 0
	v_exp_f32_e32 v240, v240
	v_sub_f32_e32 v202, v123, v247
	v_fmac_f32_e32 v243, v105, v236
	v_cndmask_b32_e64 v237, v237, 0, s[54:55]
	v_exp_f32_e32 v241, v241
	v_fmac_f32_e32 v243, v106, v237
	v_cndmask_b32_e64 v238, v238, 0, s[56:57]
	v_exp_f32_e32 v202, v202
	v_fmac_f32_e32 v243, v107, v238
	v_cndmask_b32_e64 v239, v239, 0, s[58:59]
	v_fmac_f32_e32 v243, v92, v239
	v_cndmask_b32_e64 v240, v240, 0, s[60:61]
	v_fmac_f32_e32 v243, v93, v240
	v_cndmask_b32_e64 v241, v241, 0, s[62:63]
	v_fmac_f32_e32 v243, v94, v241
	v_cndmask_b32_e64 v242, v202, 0, s[64:65]
	v_fmac_f32_e32 v243, v95, v242
	v_mov_b32_e32 v202, v243
	s_nop 1
	v_permlane16_swap_b32_e32 v243, v202
	v_add_f32_e32 v243, v243, v202
	v_mov_b32_e32 v244, v243
	s_nop 1
	v_permlane32_swap_b32_e32 v243, v244
	s_and_saveexec_b64 s[86:87], s[8:9]
	s_cbranch_execz .LBB0_222
	v_add_f32_e32 v202, v243, v244
	ds_write_b32 v199, v202 offset:128
.LBB0_222:
	s_or_b64 exec, exec, s[86:87]
	v_sub_f32_e32 v124, v124, v248
	v_sub_f32_e32 v125, v125, v248
	v_sub_f32_e32 v126, v126, v248
	v_exp_f32_e32 v124, v124
	v_exp_f32_e32 v125, v125
	v_sub_f32_e32 v127, v127, v248
	v_exp_f32_e32 v126, v126
	v_sub_f32_e32 v120, v120, v248
	v_exp_f32_e32 v127, v127
	v_sub_f32_e32 v121, v121, v248
	v_cndmask_b32_e64 v124, v124, 0, s[66:67]
	v_exp_f32_e32 v120, v120
	v_sub_f32_e32 v122, v122, v248
	v_cndmask_b32_e64 v125, 0, v125, s[68:69]
	v_fma_f32 v243, v96, v124, 0
	v_exp_f32_e32 v121, v121
	v_sub_f32_e32 v123, v123, v248
	v_fmac_f32_e32 v243, v97, v125
	v_cndmask_b32_e64 v126, v126, 0, s[70:71]
	v_exp_f32_e32 v122, v122
	v_fmac_f32_e32 v243, v98, v126
	v_cndmask_b32_e64 v127, v127, 0, s[72:73]
	v_exp_f32_e32 v123, v123
	v_fmac_f32_e32 v243, v99, v127
	v_cndmask_b32_e64 v120, v120, 0, s[74:75]
	v_fmac_f32_e32 v243, v88, v120
	v_cndmask_b32_e64 v121, v121, 0, s[76:77]
	v_fmac_f32_e32 v243, v89, v121
	v_cndmask_b32_e64 v122, v122, 0, s[78:79]
	v_fmac_f32_e32 v243, v90, v122
	v_cndmask_b32_e64 v123, v123, 0, s[80:81]
	v_fmac_f32_e32 v243, v91, v123
	v_mov_b32_e32 v202, v243
	s_nop 1
	v_permlane16_swap_b32_e32 v243, v202
	v_add_f32_e32 v243, v243, v202
	v_mov_b32_e32 v244, v243
	s_nop 1
	v_permlane32_swap_b32_e32 v243, v244
	s_and_saveexec_b64 s[86:87], s[8:9]
	s_cbranch_execz .LBB0_224
	v_add_f32_e32 v202, v243, v244
	ds_write_b32 v199, v202 offset:192
